# v019 + lgkmcnt(0) at each PV block entry so no more than 12 LDS reads are ever outstanding (robustness, timing-neutral)
# speedup vs baseline: 1.0404x; 1.0060x over previous
.LBB0_597:
	s_setprio 0
	s_waitcnt lgkmcnt(0)
	s_and_b64 vcc, exec, s[98:99]
	v_cvt_pk_bf16_f32 v96, v112, v113
	v_cvt_pk_bf16_f32 v97, v116, v115
	v_cvt_pk_bf16_f32 v98, v118, v119
	v_cvt_pk_bf16_f32 v99, v120, v117
	v_cvt_pk_bf16_f32 v100, v114, v121
	v_cvt_pk_bf16_f32 v101, v122, v123
	v_cvt_pk_bf16_f32 v102, v124, v125
	v_cvt_pk_bf16_f32 v103, v126, v127
	ds_read_b64_tr_b16 v[104:105], v244 offset:61440
	ds_read_b64_tr_b16 v[106:107], v244 offset:63488
	ds_read_b64_tr_b16 v[108:109], v245 offset:61440
	ds_read_b64_tr_b16 v[110:111], v245 offset:63488
	ds_read_b64_tr_b16 v[112:113], v246 offset:61440
	ds_read_b64_tr_b16 v[114:115], v246 offset:63488
	ds_read_b64_tr_b16 v[116:117], v247 offset:61440
	ds_read_b64_tr_b16 v[118:119], v247 offset:63488
	s_add_i32 s65, s65, 1
	s_add_u32 s36, s36, 0x10000
	s_addc_u32 s37, s37, 0
	s_addk_i32 s69, 0x4000
	s_add_i32 s70, s70, 64
	s_add_u32 s38, s38, 0x10000
	s_addc_u32 s39, s39, 0
	s_add_i32 s71, s71, 1
	s_add_i32 s46, s46, 1
	v_add_f32_e32 v162, v163, v162
	s_cbranch_vccz .Lat_lower
	s_mul_i32 s0, s65, 0xab
	s_bfe_u32 s0, s0, 0x70009
	s_mul_i32 s0, s0, 3
	s_sub_i32 s0, s65, s0
	s_and_b32 s0, s0, 0xff
	s_lshl_b32 s0, s0, 14
	s_add_i32 s0, s82, s0
	s_sub_u32 s100, s36, 0x4000
	s_subb_u32 s101, s37, 0
	s_waitcnt vmcnt(0) lgkmcnt(0)
	s_barrier
	v_mfma_f32_32x32x16_bf16 v[48:63], v[228:231], v[96:99], v[48:63]
	s_mov_b32 m0, s0
	s_add_i32 s1, s0, 0x2000
	global_load_lds_dwordx4 v174, s[36:37]
	v_mfma_f32_32x32x16_bf16 v[32:47], v[232:235], v[96:99], v[32:47]
	s_mov_b32 m0, s1
	s_add_i32 s1, s0, 0xfffff000
	global_load_lds_dwordx4 v180, s[36:37]
	v_mfma_f32_32x32x16_bf16 v[16:31], v[236:239], v[96:99], v[16:31]
	s_mov_b32 m0, s1
	s_add_i32 s1, s1, 0x2000
	global_load_lds_dwordx4 v174, s[100:101]
	v_mfma_f32_32x32x16_bf16 v[0:15], v[240:243], v[96:99], v[0:15]
	s_mov_b32 m0, s1
	s_and_b32 s0, s69, 0x4000
	s_add_i32 s0, s83, s0
	global_load_lds_dwordx4 v180, s[100:101]
	v_mfma_f32_32x32x16_bf16 v[48:63], v[104:107], v[100:103], v[48:63]
	s_mov_b32 m0, s0
	s_sub_u32 s100, s38, 0x4000
	s_subb_u32 s101, s39, 0
	s_add_i32 s1, s0, 0x2000
	global_load_lds_dwordx4 v175, s[38:39]
	v_mfma_f32_32x32x16_bf16 v[32:47], v[108:111], v[100:103], v[32:47]
	s_mov_b32 m0, s1
	s_add_i32 s1, s0, 0xfffff000
	global_load_lds_dwordx4 v181, s[38:39]
	v_mfma_f32_32x32x16_bf16 v[16:31], v[112:115], v[100:103], v[16:31]
	s_mov_b32 m0, s1
	s_add_i32 s1, s1, 0x2000
	global_load_lds_dwordx4 v175, s[100:101]
	v_mfma_f32_32x32x16_bf16 v[0:15], v[116:119], v[100:103], v[0:15]
	s_mov_b32 m0, s1
	s_nop 0
	global_load_lds_dwordx4 v181, s[100:101]
	s_branch .Lat_join

.LBB0_607:
	s_setprio 0
	s_waitcnt lgkmcnt(0)
	v_cvt_pk_bf16_f32 v80, v112, v113
	v_cvt_pk_bf16_f32 v81, v114, v115
	v_cvt_pk_bf16_f32 v82, v116, v117
	v_cvt_pk_bf16_f32 v83, v118, v119
	ds_read_b64_tr_b16 v[88:89], v244 offset:53248
	ds_read_b64_tr_b16 v[90:91], v244 offset:55296
	ds_read_b64_tr_b16 v[92:93], v245 offset:53248
	ds_read_b64_tr_b16 v[94:95], v245 offset:55296
	v_cvt_pk_bf16_f32 v84, v120, v121
	v_cvt_pk_bf16_f32 v85, v122, v123
	v_cvt_pk_bf16_f32 v86, v124, v125
	v_cvt_pk_bf16_f32 v87, v126, v127
	ds_read_b64_tr_b16 v[112:113], v246 offset:53248
	ds_read_b64_tr_b16 v[114:115], v246 offset:55296
	ds_read_b64_tr_b16 v[116:117], v247 offset:53248
	ds_read_b64_tr_b16 v[118:119], v247 offset:55296
	s_waitcnt lgkmcnt(8)
	v_mfma_f32_32x32x16_bf16 v[48:63], v[228:231], v[80:83], v[48:63]
	s_cmp_gt_u32 s70, s66
	s_cselect_b64 s[0:1], -1, 0
	s_and_b64 s[8:9], s[0:1], exec
	s_cselect_b32 s61, 2, 1
	v_mfma_f32_32x32x16_bf16 v[32:47], v[232:235], v[80:83], v[32:47]
	s_cmp_gt_i32 s70, s68
	s_cselect_b64 vcc, -1, 0
	s_and_b64 s[8:9], vcc, exec
	s_cselect_b32 s61, s61, 0
	v_mfma_f32_32x32x16_bf16 v[16:31], v[236:239], v[80:83], v[16:31]
	s_cmp_eq_u32 s61, s60
	v_mfma_f32_32x32x16_bf16 v[0:15], v[240:243], v[80:83], v[0:15]
	s_waitcnt lgkmcnt(6)
	v_mfma_f32_32x32x16_bf16 v[48:63], v[88:91], v[84:87], v[48:63]
	s_waitcnt lgkmcnt(4)
	v_mfma_f32_32x32x16_bf16 v[32:47], v[92:95], v[84:87], v[32:47]
	s_waitcnt lgkmcnt(2)
	v_mfma_f32_32x32x16_bf16 v[16:31], v[112:115], v[84:87], v[16:31]
	s_waitcnt lgkmcnt(0)
	v_mfma_f32_32x32x16_bf16 v[0:15], v[116:119], v[84:87], v[0:15]
	s_cbranch_scc1 .LBB0_609
	s_and_b64 s[8:9], vcc, s[0:1]
	v_cndmask_b32_e64 v80, 0, v161, s[8:9]
	s_cmp_eq_u32 s60, 0
	v_cndmask_b32_e32 v80, v160, v80, vcc
	s_cselect_b64 vcc, -1, 0
	s_cmp_eq_u32 s60, 2
	s_cselect_b64 s[8:9], -1, 0
	v_cndmask_b32_e64 v81, 0, v161, s[8:9]
	v_cndmask_b32_e32 v81, v81, v160, vcc
	v_sub_f32_e32 v80, v80, v81
	v_pk_add_f32 v[78:79], v[80:81], v[78:79] op_sel_hi:[0,1]
	v_pk_add_f32 v[76:77], v[80:81], v[76:77] op_sel_hi:[0,1]
	v_pk_add_f32 v[74:75], v[80:81], v[74:75] op_sel_hi:[0,1]
	v_pk_add_f32 v[72:73], v[80:81], v[72:73] op_sel_hi:[0,1]
	v_pk_add_f32 v[70:71], v[80:81], v[70:71] op_sel_hi:[0,1]
	v_pk_add_f32 v[68:69], v[80:81], v[68:69] op_sel_hi:[0,1]
	v_pk_add_f32 v[66:67], v[80:81], v[66:67] op_sel_hi:[0,1]
	v_pk_add_f32 v[64:65], v[80:81], v[64:65] op_sel_hi:[0,1]
	s_branch .LBB0_610
